# lever 4: one static s_setprio 1 for waves 4-7 at kernel entry, all per-segment s_setprio flips removed (also in the two small pool GEMM loops)
# baseline (speedup 1.0000x reference)
; #define LAS __attribute__((address_space(3)))
; __device__ __forceinline__ unsigned xb_add(unsigned* p, unsigned v) { return __hip_atomic_fetch_add(p, v, __ATOMIC_RELAXED, __HIP_MEMORY_SCOPE_AGENT); }
; __device__ __forceinline__ unsigned xb_xcc_id() { return (unsigned)__builtin_amdgcn_s_getreg((3 << 11) | 20) & 0xFu; }
; __device__ __forceinline__ XcdBarrier xcd_barrier_post(unsigned* bar, volatile LAS unsigned* st) {
;     XcdBarrier b; b.bar = bar; b.x = xb_xcc_id(); b.st = st;
;     if (threadIdx.x == 0) (void)xb_add(&bar[XB_XCNT(b.x)], 1u);
;     return b;
; __global__ void __launch_bounds__(512, 2) fwd_megakernel(Params p) {
;     extern __shared__ __attribute__((aligned(16))) unsigned char lds_raw[];
;     LAS unsigned char* lds = (LAS unsigned char*)lds_raw;
;     LAS float* rs = (LAS float*)(lds + RS_OFF);
;     cg::grid_group grid = cg::this_grid();
;     { volatile LAS unsigned* misc = (volatile LAS unsigned*)(lds + MISC_OFF); if (threadIdx.x < 2) misc[threadIdx.x] = 0u; }
;     __syncthreads();
;     const XcdBarrier bar = xcd_barrier_post((unsigned*)(p.ws + WS_CTL), (volatile LAS unsigned*)(lds + MISC_OFF));
_Z14fwd_megakernel6Params:
	v_readfirstlane_b32 s100, v0
	s_nop 3
	s_and_b32 s100, s100, 0x3ff
	s_lshr_b32 s100, s100, 6
	s_cmp_ge_u32 s100, 4
	s_cbranch_scc0 .Lprio_done
	s_setprio 1
.Lprio_done:
	s_load_dword s3, s[0:1], 0x98
	s_load_dwordx4 s[4:7], s[0:1], 0x80
	s_load_dwordx2 s[56:57], s[0:1], 0x90
	s_add_u32 s28, s0, 0x90
	v_and_b32_e32 v210, 0x3ff, v0
	s_waitcnt lgkmcnt(0)
	v_writelane_b32 v251, s3, 0
	v_writelane_b32 v251, s4, 1
	s_addc_u32 s29, s1, 0
	v_cmp_gt_u32_e32 vcc, 2, v210
	v_writelane_b32 v251, s5, 2
	v_writelane_b32 v251, s6, 3
	v_writelane_b32 v251, s7, 4
	s_and_saveexec_b64 s[4:5], vcc
	v_lshl_add_u32 v1, v210, 2, 0
	v_add_u32_e32 v1, 0x23c00, v1
	v_mov_b32_e32 v2, 0
	ds_write_b32 v1, v2
	s_or_b64 exec, exec, s[4:5]
	s_load_dwordx4 s[4:7], s[0:1], 0x80
	s_waitcnt lgkmcnt(0)
	s_barrier
	s_getreg_b32 s3, hwreg(HW_REG_XCC_ID, 0, 4)
	s_add_u32 s36, s6, 0x1f500000
	s_addc_u32 s37, s7, 0
	s_and_b32 s52, s3, 15
	v_cmp_ne_u32_e64 s[4:5], 0, v210
	v_cmp_eq_u32_e64 s[8:9], 0, v210
	s_mov_b64 s[6:7], exec
	s_nop 0
	v_writelane_b32 v251, s8, 5
	s_nop 1
	v_writelane_b32 v251, s9, 6
	s_and_b64 s[8:9], s[6:7], s[8:9]
	s_mov_b64 exec, s[8:9]
	s_cbranch_execz .LBB0_5
	s_mov_b64 s[8:9], exec
	v_mbcnt_lo_u32_b32 v1, s8, 0
	v_mbcnt_hi_u32_b32 v1, s9, v1
	v_cmp_eq_u32_e32 vcc, 0, v1
	s_and_b64 s[10:11], exec, vcc
	s_mov_b64 exec, s[10:11]
	s_cbranch_execz .LBB0_5
	s_lshl_b32 s3, s52, 8
	s_bcnt1_i32_b64 s8, s[8:9]
	v_mov_b32_e32 v1, s3
	v_mov_b32_e32 v2, s8
	global_atomic_add v1, v2, s[36:37] offset:1024

; #define PG8_STAGE(bufoff, gbase, voff) do { _Pragma("unroll") for (int _i = 0; _i < 2; ++_i) \
;         __builtin_amdgcn_global_load_lds((const unsigned*)((const char*)(gbase) + (voff)[_i]), (LAS unsigned*)(lds + (bufoff) + ldsw + _i * 8192), 16, 0, 0); } while (0)
; #define PG8_LDA(dst, b, h) do { _Pragma("unroll") for (int m = 0; m < 4; ++m) _Pragma("unroll") for (int k = 0; k < 2; ++k) dst[m][k] = *(const LAS bf16x8*)(lds + PG8_SA(b, h) + aoff + m * 2048 + k * 1024); } while (0)
; #define PG8_LDB(dst, b, h) do { _Pragma("unroll") for (int n = 0; n < 2; ++n) _Pragma("unroll") for (int k = 0; k < 2; ++k) dst[n][k] = *(const LAS bf16x8*)(lds + PG8_SB(b, h) + boff + n * 2048 + k * 1024); } while (0)
; #define PG8_MMA(ai, bj, At, Bt) do { __builtin_amdgcn_s_setprio(1); _Pragma("unroll") for (int m = 0; m < 4; ++m) _Pragma("unroll") for (int n = 0; n < 2; ++n) _Pragma("unroll") for (int k = 0; k < 2; ++k) \
;         acc[ai][bj][m][n] = __builtin_amdgcn_mfma_f32_16x16x32_bf16(Bt[n][k], At[m][k], acc[ai][bj][m][n], 0, 0, 0); __builtin_amdgcn_s_setprio(0); } while (0)
; #define PG8_WAIT_V(n) asm volatile("s_waitcnt vmcnt(" #n ")" ::: "memory")
; #define PG8_WAIT_L(n) asm volatile("s_waitcnt lgkmcnt(" #n ")" ::: "memory")
; #define PG8_BAR __builtin_amdgcn_s_barrier()
; #define PG8_SCHED __builtin_amdgcn_sched_barrier(0)
; template <class Epi, class Sched>
; __device__ __forceinline__ void gemm_phase(LAS unsigned char* lds, const Gemm g, const Sched& S, const Epi& E) {
;     ...
;             PG8_LDB(B0, 0, 0); PG8_LDB(B1, 0, 1); PG8_SCHED; PG8_LDA(At, 0, 0); PG8_STAGE(PG8_SA(1, 1), a1 + hstepA, voffA);
;             PG8_WAIT_V(8); PG8_WAIT_L(0); PG8_BAR; PG8_MMA(0, 0, At, B0); PG8_MMA(0, 1, At, B1); PG8_BAR; PG8_SCHED;
;             PG8_LDA(At, 0, 1); PG8_STAGE(PG8_SB(0, 0), b2, voffB); PG8_STAGE(PG8_SB(0, 1), b2 + hstepB, voffB); PG8_STAGE(PG8_SA(0, 0), a2, voffA);
;             PG8_WAIT_V(8); PG8_WAIT_L(0); PG8_BAR; PG8_MMA(1, 0, At, B0); PG8_MMA(1, 1, At, B1); PG8_BAR; PG8_SCHED;
.LBB0_666:
	s_add_i32 vcc_lo, s20, 2
	s_add_u32 s90, s18, 0x80
	s_addc_u32 s21, s19, 0
	s_add_i32 vcc_hi, 0, 0x10000
	s_cmp_eq_u32 s48, s20
	s_cselect_b32 s21, s71, s21
	s_cselect_b32 s20, s70, s90
	s_cselect_b32 s91, s85, s87
	s_cselect_b32 s90, s84, s86
	s_add_i32 s92, 0, 0x14000
	v_add_u32_e32 v154, vcc_hi, v170
	v_add_u32_e32 v173, s92, v170
	ds_read_b128 v[130:133], v154
	ds_read_b128 v[146:149], v154 offset:1024
	ds_read_b128 v[150:153], v154 offset:2048
	ds_read_b128 v[154:157], v154 offset:3072
	ds_read_b128 v[158:161], v173
	ds_read_b128 v[162:165], v173 offset:1024
	ds_read_b128 v[166:169], v173 offset:2048
	ds_read_b128 v[190:193], v173 offset:3072
	v_lshl_add_u64 v[234:235], s[18:19], 0, v[142:143]
	s_add_i32 m0, s35, 0xc000
	ds_read_b128 v[194:197], v172
	ds_read_b128 v[198:201], v172 offset:1024
	ds_read_b128 v[202:205], v172 offset:2048
	ds_read_b128 v[206:209], v172 offset:3072
	ds_read_b128 v[218:221], v172 offset:4096
	ds_read_b128 v[222:225], v172 offset:5120
	ds_read_b128 v[226:229], v172 offset:6144
	ds_read_b128 v[230:233], v172 offset:7168
	global_load_lds_dwordx4 v[234:235], off
	v_lshl_add_u64 v[234:235], s[18:19], 0, v[144:145]
	s_add_i32 m0, s35, 0xe000
	s_nop 0
	global_load_lds_dwordx4 v[234:235], off
	s_waitcnt vmcnt(8)
	s_waitcnt lgkmcnt(0)
	s_barrier
	s_waitcnt lgkmcnt(0)
	v_mfma_f32_16x16x32_bf16 v[26:29], v[130:133], v[194:197], v[26:29]
	v_mfma_f32_16x16x32_bf16 v[106:109], v[150:153], v[194:197], v[106:109]
	v_mfma_f32_16x16x32_bf16 v[22:25], v[130:133], v[202:205], v[22:25]
	v_mfma_f32_16x16x32_bf16 v[94:97], v[150:153], v[202:205], v[94:97]
	v_mfma_f32_16x16x32_bf16 v[14:17], v[130:133], v[218:221], v[14:17]
	v_mfma_f32_16x16x32_bf16 v[82:85], v[150:153], v[218:221], v[82:85]
	v_mfma_f32_16x16x32_bf16 v[10:13], v[130:133], v[226:229], v[10:13]
	v_mfma_f32_16x16x32_bf16 v[70:73], v[150:153], v[226:229], v[70:73]
	v_mfma_f32_16x16x32_bf16 v[26:29], v[146:149], v[198:201], v[26:29]
	v_mfma_f32_16x16x32_bf16 v[106:109], v[154:157], v[198:201], v[106:109]
	v_mfma_f32_16x16x32_bf16 v[22:25], v[146:149], v[206:209], v[22:25]
	v_mfma_f32_16x16x32_bf16 v[94:97], v[154:157], v[206:209], v[94:97]
	v_mfma_f32_16x16x32_bf16 v[14:17], v[146:149], v[222:225], v[14:17]
	v_mfma_f32_16x16x32_bf16 v[82:85], v[154:157], v[222:225], v[82:85]
	v_mfma_f32_16x16x32_bf16 v[10:13], v[146:149], v[230:233], v[10:13]
	v_mfma_f32_16x16x32_bf16 v[70:73], v[154:157], v[230:233], v[70:73]
	v_mfma_f32_16x16x32_bf16 v[118:121], v[158:161], v[194:197], v[118:121]
	v_mfma_f32_16x16x32_bf16 v[126:129], v[166:169], v[194:197], v[126:129]
	v_mfma_f32_16x16x32_bf16 v[110:113], v[158:161], v[202:205], v[110:113]
	v_mfma_f32_16x16x32_bf16 v[122:125], v[166:169], v[202:205], v[122:125]
	v_mfma_f32_16x16x32_bf16 v[98:101], v[158:161], v[218:221], v[98:101]
	v_mfma_f32_16x16x32_bf16 v[114:117], v[166:169], v[218:221], v[114:117]
	v_mfma_f32_16x16x32_bf16 v[86:89], v[158:161], v[226:229], v[86:89]
	v_mfma_f32_16x16x32_bf16 v[102:105], v[166:169], v[226:229], v[102:105]
	v_mfma_f32_16x16x32_bf16 v[118:121], v[162:165], v[198:201], v[118:121]
	v_mfma_f32_16x16x32_bf16 v[126:129], v[190:193], v[198:201], v[126:129]
	v_mfma_f32_16x16x32_bf16 v[110:113], v[162:165], v[206:209], v[110:113]
	v_mfma_f32_16x16x32_bf16 v[122:125], v[190:193], v[206:209], v[122:125]
	v_mfma_f32_16x16x32_bf16 v[98:101], v[162:165], v[222:225], v[98:101]
	v_mfma_f32_16x16x32_bf16 v[114:117], v[190:193], v[222:225], v[114:117]
	v_mfma_f32_16x16x32_bf16 v[86:89], v[162:165], v[230:233], v[86:89]
	v_mfma_f32_16x16x32_bf16 v[102:105], v[190:193], v[230:233], v[102:105]
	s_barrier
	s_add_i32 s93, vcc_hi, s34
	v_lshl_add_u64 v[234:235], s[90:91], 0, v[136:137]
	s_mov_b32 m0, s93
	ds_read_b128 v[194:197], v172 offset:16384
	ds_read_b128 v[198:201], v172 offset:17408
	ds_read_b128 v[202:205], v172 offset:18432
	ds_read_b128 v[206:209], v172 offset:19456
	ds_read_b128 v[218:221], v172 offset:20480
	ds_read_b128 v[222:225], v172 offset:21504
	ds_read_b128 v[226:229], v172 offset:22528
	ds_read_b128 v[230:233], v172 offset:23552
	global_load_lds_dwordx4 v[234:235], off
	s_add_i32 m0, s93, 0x2000
	v_lshl_add_u64 v[236:237], s[90:91], 0, v[140:141]
	s_add_u32 s90, s90, s29
	s_addc_u32 s91, s91, 0
	s_add_i32 s92, s92, s34
	global_load_lds_dwordx4 v[236:237], off
	v_lshl_add_u64 v[238:239], s[90:91], 0, v[136:137]
	s_mov_b32 m0, s92
	v_lshl_add_u64 v[240:241], s[90:91], 0, v[140:141]
	global_load_lds_dwordx4 v[238:239], off
	s_add_i32 m0, s92, 0x2000
	v_lshl_add_u64 v[242:243], s[20:21], 0, v[134:135]
	global_load_lds_dwordx4 v[240:241], off
	s_mov_b32 m0, s35
	v_lshl_add_u64 v[244:245], s[20:21], 0, v[138:139]
	global_load_lds_dwordx4 v[242:243], off
	s_mov_b32 m0, s40
	s_nop 0
	global_load_lds_dwordx4 v[244:245], off
	s_waitcnt vmcnt(8)
	s_waitcnt lgkmcnt(0)
	s_barrier
; #define PG8_STAGE(bufoff, gbase, voff) do { _Pragma("unroll") for (int _i = 0; _i < 2; ++_i) \
;         __builtin_amdgcn_global_load_lds((const unsigned*)((const char*)(gbase) + (voff)[_i]), (LAS unsigned*)(lds + (bufoff) + ldsw + _i * 8192), 16, 0, 0); } while (0)
; #define PG8_LDA(dst, b, h) do { _Pragma("unroll") for (int m = 0; m < 4; ++m) _Pragma("unroll") for (int k = 0; k < 2; ++k) dst[m][k] = *(const LAS bf16x8*)(lds + PG8_SA(b, h) + aoff + m * 2048 + k * 1024); } while (0)
; #define PG8_LDB(dst, b, h) do { _Pragma("unroll") for (int n = 0; n < 2; ++n) _Pragma("unroll") for (int k = 0; k < 2; ++k) dst[n][k] = *(const LAS bf16x8*)(lds + PG8_SB(b, h) + boff + n * 2048 + k * 1024); } while (0)
; #define PG8_MMA(ai, bj, At, Bt) do { __builtin_amdgcn_s_setprio(1); _Pragma("unroll") for (int m = 0; m < 4; ++m) _Pragma("unroll") for (int n = 0; n < 2; ++n) _Pragma("unroll") for (int k = 0; k < 2; ++k) \
;         acc[ai][bj][m][n] = __builtin_amdgcn_mfma_f32_16x16x32_bf16(Bt[n][k], At[m][k], acc[ai][bj][m][n], 0, 0, 0); __builtin_amdgcn_s_setprio(0); } while (0)
; #define PG8_WAIT_V(n) asm volatile("s_waitcnt vmcnt(" #n ")" ::: "memory")
; #define PG8_WAIT_L(n) asm volatile("s_waitcnt lgkmcnt(" #n ")" ::: "memory")
; #define PG8_BAR __builtin_amdgcn_s_barrier()
; #define PG8_SCHED __builtin_amdgcn_sched_barrier(0)
; template <class Epi, class Sched>
; __device__ __forceinline__ void gemm_phase(LAS unsigned char* lds, const Gemm g, const Sched& S, const Epi& E) {
;     ...
;             PG8_LDA(At, 0, 1); PG8_STAGE(PG8_SB(0, 0), b2, voffB); PG8_STAGE(PG8_SB(0, 1), b2 + hstepB, voffB); PG8_STAGE(PG8_SA(0, 0), a2, voffA);
;             PG8_WAIT_V(8); PG8_WAIT_L(0); PG8_BAR; PG8_MMA(1, 0, At, B0); PG8_MMA(1, 1, At, B1); PG8_BAR; PG8_SCHED;
;             PG8_LDB(B0, 1, 0); PG8_LDB(B1, 1, 1); PG8_SCHED; PG8_LDA(At, 1, 0); PG8_STAGE(PG8_SA(0, 1), a2 + hstepA, voffA);
;             PG8_WAIT_V(8); PG8_WAIT_L(0); PG8_BAR; PG8_MMA(0, 0, At, B0); PG8_MMA(0, 1, At, B1); PG8_BAR; PG8_SCHED;
	s_waitcnt lgkmcnt(0)
	v_mfma_f32_16x16x32_bf16 v[6:9], v[130:133], v[194:197], v[6:9]
	v_mfma_f32_16x16x32_bf16 v[58:61], v[150:153], v[194:197], v[58:61]
	v_mfma_f32_16x16x32_bf16 v[2:5], v[130:133], v[202:205], v[2:5]
	v_mfma_f32_16x16x32_bf16 v[46:49], v[150:153], v[202:205], v[46:49]
	v_mfma_f32_16x16x32_bf16 v[30:33], v[130:133], v[218:221], v[30:33]
	v_mfma_f32_16x16x32_bf16 v[38:41], v[150:153], v[218:221], v[38:41]
	v_mfma_f32_16x16x32_bf16 v[18:21], v[130:133], v[226:229], v[18:21]
	v_mfma_f32_16x16x32_bf16 v[34:37], v[150:153], v[226:229], v[34:37]
	v_mfma_f32_16x16x32_bf16 v[6:9], v[146:149], v[198:201], v[6:9]
	v_mfma_f32_16x16x32_bf16 v[58:61], v[154:157], v[198:201], v[58:61]
	v_mfma_f32_16x16x32_bf16 v[2:5], v[146:149], v[206:209], v[2:5]
	v_mfma_f32_16x16x32_bf16 v[46:49], v[154:157], v[206:209], v[46:49]
	v_mfma_f32_16x16x32_bf16 v[30:33], v[146:149], v[222:225], v[30:33]
	v_mfma_f32_16x16x32_bf16 v[38:41], v[154:157], v[222:225], v[38:41]
	v_mfma_f32_16x16x32_bf16 v[18:21], v[146:149], v[230:233], v[18:21]
	v_mfma_f32_16x16x32_bf16 v[34:37], v[154:157], v[230:233], v[34:37]
	v_mfma_f32_16x16x32_bf16 v[74:77], v[158:161], v[194:197], v[74:77]
	v_mfma_f32_16x16x32_bf16 v[90:93], v[166:169], v[194:197], v[90:93]
	v_mfma_f32_16x16x32_bf16 v[62:65], v[158:161], v[202:205], v[62:65]
	v_mfma_f32_16x16x32_bf16 v[78:81], v[166:169], v[202:205], v[78:81]
	v_mfma_f32_16x16x32_bf16 v[50:53], v[158:161], v[218:221], v[50:53]
	v_mfma_f32_16x16x32_bf16 v[66:69], v[166:169], v[218:221], v[66:69]
	v_mfma_f32_16x16x32_bf16 v[42:45], v[158:161], v[226:229], v[42:45]
	v_mfma_f32_16x16x32_bf16 v[54:57], v[166:169], v[226:229], v[54:57]
	v_mfma_f32_16x16x32_bf16 v[74:77], v[162:165], v[198:201], v[74:77]
	v_mfma_f32_16x16x32_bf16 v[90:93], v[190:193], v[198:201], v[90:93]
	v_mfma_f32_16x16x32_bf16 v[62:65], v[162:165], v[206:209], v[62:65]
	v_mfma_f32_16x16x32_bf16 v[78:81], v[190:193], v[206:209], v[78:81]
	v_mfma_f32_16x16x32_bf16 v[50:53], v[162:165], v[222:225], v[50:53]
	v_mfma_f32_16x16x32_bf16 v[66:69], v[190:193], v[222:225], v[66:69]
	v_mfma_f32_16x16x32_bf16 v[42:45], v[162:165], v[230:233], v[42:45]
	v_mfma_f32_16x16x32_bf16 v[54:57], v[190:193], v[230:233], v[54:57]
	s_barrier
	s_add_i32 s90, 0, 0x18000
	s_add_i32 s91, 0, 0x1c000
	v_add_u32_e32 v154, s90, v170
	v_add_u32_e32 v173, s91, v170
	ds_read_b128 v[130:133], v154
	ds_read_b128 v[146:149], v154 offset:1024
	ds_read_b128 v[150:153], v154 offset:2048
	ds_read_b128 v[154:157], v154 offset:3072
	ds_read_b128 v[158:161], v173
	ds_read_b128 v[162:165], v173 offset:1024
	ds_read_b128 v[166:169], v173 offset:2048
	ds_read_b128 v[190:193], v173 offset:3072
	s_add_u32 s20, s20, s80
	s_addc_u32 s21, s21, 0
	s_mov_b32 m0, s41
	v_lshl_add_u64 v[246:247], s[20:21], 0, v[134:135]
	ds_read_b128 v[194:197], v172 offset:32768
	ds_read_b128 v[198:201], v172 offset:33792
	ds_read_b128 v[202:205], v172 offset:34816
	ds_read_b128 v[206:209], v172 offset:35840
	ds_read_b128 v[218:221], v172 offset:36864
	ds_read_b128 v[222:225], v172 offset:37888
	ds_read_b128 v[226:229], v172 offset:38912
	ds_read_b128 v[230:233], v172 offset:39936
	global_load_lds_dwordx4 v[246:247], off
	v_lshl_add_u64 v[246:247], s[20:21], 0, v[138:139]
	s_mov_b32 m0, s8
	s_nop 0
	global_load_lds_dwordx4 v[246:247], off
	s_waitcnt vmcnt(8)
	s_waitcnt lgkmcnt(0)
	s_barrier
	s_waitcnt lgkmcnt(0)
	v_mfma_f32_16x16x32_bf16 v[26:29], v[130:133], v[194:197], v[26:29]
	v_mfma_f32_16x16x32_bf16 v[106:109], v[150:153], v[194:197], v[106:109]
	v_mfma_f32_16x16x32_bf16 v[22:25], v[130:133], v[202:205], v[22:25]
	v_mfma_f32_16x16x32_bf16 v[94:97], v[150:153], v[202:205], v[94:97]
	v_mfma_f32_16x16x32_bf16 v[14:17], v[130:133], v[218:221], v[14:17]
	v_mfma_f32_16x16x32_bf16 v[82:85], v[150:153], v[218:221], v[82:85]
	v_mfma_f32_16x16x32_bf16 v[10:13], v[130:133], v[226:229], v[10:13]
	v_mfma_f32_16x16x32_bf16 v[70:73], v[150:153], v[226:229], v[70:73]
	v_mfma_f32_16x16x32_bf16 v[26:29], v[146:149], v[198:201], v[26:29]
	v_mfma_f32_16x16x32_bf16 v[106:109], v[154:157], v[198:201], v[106:109]
	v_mfma_f32_16x16x32_bf16 v[22:25], v[146:149], v[206:209], v[22:25]
	v_mfma_f32_16x16x32_bf16 v[94:97], v[154:157], v[206:209], v[94:97]
	v_mfma_f32_16x16x32_bf16 v[14:17], v[146:149], v[222:225], v[14:17]
	v_mfma_f32_16x16x32_bf16 v[82:85], v[154:157], v[222:225], v[82:85]
	v_mfma_f32_16x16x32_bf16 v[10:13], v[146:149], v[230:233], v[10:13]
	v_mfma_f32_16x16x32_bf16 v[70:73], v[154:157], v[230:233], v[70:73]
	v_mfma_f32_16x16x32_bf16 v[118:121], v[158:161], v[194:197], v[118:121]
	v_mfma_f32_16x16x32_bf16 v[126:129], v[166:169], v[194:197], v[126:129]
	v_mfma_f32_16x16x32_bf16 v[110:113], v[158:161], v[202:205], v[110:113]
	v_mfma_f32_16x16x32_bf16 v[122:125], v[166:169], v[202:205], v[122:125]
	v_mfma_f32_16x16x32_bf16 v[98:101], v[158:161], v[218:221], v[98:101]
	v_mfma_f32_16x16x32_bf16 v[114:117], v[166:169], v[218:221], v[114:117]
	v_mfma_f32_16x16x32_bf16 v[86:89], v[158:161], v[226:229], v[86:89]
	v_mfma_f32_16x16x32_bf16 v[102:105], v[166:169], v[226:229], v[102:105]
	v_mfma_f32_16x16x32_bf16 v[118:121], v[162:165], v[198:201], v[118:121]
	v_mfma_f32_16x16x32_bf16 v[126:129], v[190:193], v[198:201], v[126:129]
	v_mfma_f32_16x16x32_bf16 v[110:113], v[162:165], v[206:209], v[110:113]
	v_mfma_f32_16x16x32_bf16 v[122:125], v[190:193], v[206:209], v[122:125]
	v_mfma_f32_16x16x32_bf16 v[98:101], v[162:165], v[222:225], v[98:101]
	v_mfma_f32_16x16x32_bf16 v[114:117], v[190:193], v[222:225], v[114:117]
	v_mfma_f32_16x16x32_bf16 v[86:89], v[162:165], v[230:233], v[86:89]
	v_mfma_f32_16x16x32_bf16 v[102:105], v[190:193], v[230:233], v[102:105]
	s_barrier
; #define PG8_STAGE(bufoff, gbase, voff) do { _Pragma("unroll") for (int _i = 0; _i < 2; ++_i) \
;         __builtin_amdgcn_global_load_lds((const unsigned*)((const char*)(gbase) + (voff)[_i]), (LAS unsigned*)(lds + (bufoff) + ldsw + _i * 8192), 16, 0, 0); } while (0)
; #define PG8_LDA(dst, b, h) do { _Pragma("unroll") for (int m = 0; m < 4; ++m) _Pragma("unroll") for (int k = 0; k < 2; ++k) dst[m][k] = *(const LAS bf16x8*)(lds + PG8_SA(b, h) + aoff + m * 2048 + k * 1024); } while (0)
; #define PG8_MMA(ai, bj, At, Bt) do { __builtin_amdgcn_s_setprio(1); _Pragma("unroll") for (int m = 0; m < 4; ++m) _Pragma("unroll") for (int n = 0; n < 2; ++n) _Pragma("unroll") for (int k = 0; k < 2; ++k) \
;         acc[ai][bj][m][n] = __builtin_amdgcn_mfma_f32_16x16x32_bf16(Bt[n][k], At[m][k], acc[ai][bj][m][n], 0, 0, 0); __builtin_amdgcn_s_setprio(0); } while (0)
; #define PG8_WAIT_V(n) asm volatile("s_waitcnt vmcnt(" #n ")" ::: "memory")
; #define PG8_WAIT_L(n) asm volatile("s_waitcnt lgkmcnt(" #n ")" ::: "memory")
; #define PG8_BAR __builtin_amdgcn_s_barrier()
; #define PG8_SCHED __builtin_amdgcn_sched_barrier(0)
; template <class Epi, class Sched>
; __device__ __forceinline__ void gemm_phase(LAS unsigned char* lds, const Gemm g, const Sched& S, const Epi& E) {
;     ...
;             PG8_LDA(At, 1, 1); PG8_STAGE(PG8_SB(1, 0), b3, voffB); PG8_STAGE(PG8_SB(1, 1), b3 + hstepB, voffB); PG8_STAGE(PG8_SA(1, 0), a3, voffA);
;             PG8_WAIT_V(8); PG8_WAIT_L(0); PG8_BAR; PG8_MMA(1, 0, At, B0); PG8_MMA(1, 1, At, B1); PG8_BAR; PG8_SCHED;
;         }
	s_add_i32 s20, s90, s34
	v_lshl_add_u64 v[234:235], v[234:235], 0, s[62:63]
	s_mov_b32 m0, s20
	ds_read_b128 v[194:197], v172 offset:49152
	ds_read_b128 v[198:201], v172 offset:50176
	ds_read_b128 v[202:205], v172 offset:51200
	ds_read_b128 v[206:209], v172 offset:52224
	ds_read_b128 v[218:221], v172 offset:53248
	ds_read_b128 v[222:225], v172 offset:54272
	ds_read_b128 v[226:229], v172 offset:55296
	ds_read_b128 v[230:233], v172 offset:56320
	global_load_lds_dwordx4 v[234:235], off
	v_lshl_add_u64 v[234:235], v[236:237], 0, s[62:63]
	s_add_i32 m0, s20, 0x2000
	s_add_i32 s20, s91, s34
	global_load_lds_dwordx4 v[234:235], off
	v_lshl_add_u64 v[234:235], v[238:239], 0, s[62:63]
	s_mov_b32 m0, s20
	s_nop 0
	global_load_lds_dwordx4 v[234:235], off
	v_lshl_add_u64 v[234:235], v[240:241], 0, s[62:63]
	s_add_i32 m0, s20, 0x2000
	s_nop 0
	global_load_lds_dwordx4 v[234:235], off
	v_lshl_add_u64 v[234:235], v[242:243], 0, s[62:63]
	s_mov_b32 m0, s9
	s_nop 0
	global_load_lds_dwordx4 v[234:235], off
	v_lshl_add_u64 v[234:235], v[244:245], 0, s[62:63]
	s_mov_b32 m0, s42
	s_nop 0
	global_load_lds_dwordx4 v[234:235], off
	s_waitcnt vmcnt(8)
	s_waitcnt lgkmcnt(0)
	s_barrier
	s_waitcnt lgkmcnt(0)
	v_mfma_f32_16x16x32_bf16 v[6:9], v[130:133], v[194:197], v[6:9]
	v_mfma_f32_16x16x32_bf16 v[58:61], v[150:153], v[194:197], v[58:61]
	v_mfma_f32_16x16x32_bf16 v[2:5], v[130:133], v[202:205], v[2:5]
	v_mfma_f32_16x16x32_bf16 v[46:49], v[150:153], v[202:205], v[46:49]
	v_mfma_f32_16x16x32_bf16 v[30:33], v[130:133], v[218:221], v[30:33]
	v_mfma_f32_16x16x32_bf16 v[38:41], v[150:153], v[218:221], v[38:41]
	v_mfma_f32_16x16x32_bf16 v[18:21], v[130:133], v[226:229], v[18:21]
	v_mfma_f32_16x16x32_bf16 v[34:37], v[150:153], v[226:229], v[34:37]
	v_mfma_f32_16x16x32_bf16 v[6:9], v[146:149], v[198:201], v[6:9]
	v_mfma_f32_16x16x32_bf16 v[58:61], v[154:157], v[198:201], v[58:61]
	v_mfma_f32_16x16x32_bf16 v[2:5], v[146:149], v[206:209], v[2:5]
	v_mfma_f32_16x16x32_bf16 v[46:49], v[154:157], v[206:209], v[46:49]
	v_mfma_f32_16x16x32_bf16 v[30:33], v[146:149], v[222:225], v[30:33]
	v_mfma_f32_16x16x32_bf16 v[38:41], v[154:157], v[222:225], v[38:41]
	v_mfma_f32_16x16x32_bf16 v[18:21], v[146:149], v[230:233], v[18:21]
	v_mfma_f32_16x16x32_bf16 v[34:37], v[154:157], v[230:233], v[34:37]
	v_mfma_f32_16x16x32_bf16 v[74:77], v[158:161], v[194:197], v[74:77]
	v_mfma_f32_16x16x32_bf16 v[90:93], v[166:169], v[194:197], v[90:93]
	v_mfma_f32_16x16x32_bf16 v[62:65], v[158:161], v[202:205], v[62:65]
	v_mfma_f32_16x16x32_bf16 v[78:81], v[166:169], v[202:205], v[78:81]
	v_mfma_f32_16x16x32_bf16 v[50:53], v[158:161], v[218:221], v[50:53]
	v_mfma_f32_16x16x32_bf16 v[66:69], v[166:169], v[218:221], v[66:69]
	v_mfma_f32_16x16x32_bf16 v[42:45], v[158:161], v[226:229], v[42:45]
	v_mfma_f32_16x16x32_bf16 v[54:57], v[166:169], v[226:229], v[54:57]
	v_mfma_f32_16x16x32_bf16 v[74:77], v[162:165], v[198:201], v[74:77]
	v_mfma_f32_16x16x32_bf16 v[90:93], v[190:193], v[198:201], v[90:93]
	v_mfma_f32_16x16x32_bf16 v[62:65], v[162:165], v[206:209], v[62:65]
	v_mfma_f32_16x16x32_bf16 v[78:81], v[190:193], v[206:209], v[78:81]
	v_mfma_f32_16x16x32_bf16 v[50:53], v[162:165], v[222:225], v[50:53]
	v_mfma_f32_16x16x32_bf16 v[66:69], v[190:193], v[222:225], v[66:69]
	v_mfma_f32_16x16x32_bf16 v[42:45], v[162:165], v[230:233], v[42:45]
	v_mfma_f32_16x16x32_bf16 v[54:57], v[190:193], v[230:233], v[54:57]
	s_barrier
	s_add_u32 s18, s18, 0x100
	s_addc_u32 s19, s19, 0
	s_add_u32 s86, s86, 0x100
	s_addc_u32 s87, s87, 0
	s_cmp_ge_u32 vcc_lo, s43
	s_mov_b32 s20, vcc_lo
	s_cbranch_scc0 .LBB0_666
	s_and_b64 vcc, exec, s[36:37]
	s_cbranch_vccz .LBB0_669
	s_barrier

; #define PG8_STAGE(bufoff, gbase, voff) do { _Pragma("unroll") for (int _i = 0; _i < 2; ++_i) \
;         __builtin_amdgcn_global_load_lds((const unsigned*)((const char*)(gbase) + (voff)[_i]), (LAS unsigned*)(lds + (bufoff) + ldsw + _i * 8192), 16, 0, 0); } while (0)
; #define PG8_LDA(dst, b, h) do { _Pragma("unroll") for (int m = 0; m < 4; ++m) _Pragma("unroll") for (int k = 0; k < 2; ++k) dst[m][k] = *(const LAS bf16x8*)(lds + PG8_SA(b, h) + aoff + m * 2048 + k * 1024); } while (0)
; #define PG8_LDB(dst, b, h) do { _Pragma("unroll") for (int n = 0; n < 2; ++n) _Pragma("unroll") for (int k = 0; k < 2; ++k) dst[n][k] = *(const LAS bf16x8*)(lds + PG8_SB(b, h) + boff + n * 2048 + k * 1024); } while (0)
; #define PG8_MMA(ai, bj, At, Bt) do { __builtin_amdgcn_s_setprio(1); _Pragma("unroll") for (int m = 0; m < 4; ++m) _Pragma("unroll") for (int n = 0; n < 2; ++n) _Pragma("unroll") for (int k = 0; k < 2; ++k) \
;         acc[ai][bj][m][n] = __builtin_amdgcn_mfma_f32_16x16x32_bf16(Bt[n][k], At[m][k], acc[ai][bj][m][n], 0, 0, 0); __builtin_amdgcn_s_setprio(0); } while (0)
; #define PG8_WAIT_V(n) asm volatile("s_waitcnt vmcnt(" #n ")" ::: "memory")
; #define PG8_WAIT_L(n) asm volatile("s_waitcnt lgkmcnt(" #n ")" ::: "memory")
; #define PG8_BAR __builtin_amdgcn_s_barrier()
; #define PG8_SCHED __builtin_amdgcn_sched_barrier(0)
; template <class Epi, class Sched>
; __device__ __forceinline__ void gemm_phase(LAS unsigned char* lds, const Gemm g, const Sched& S, const Epi& E) {
;     ...
;             PG8_LDB(B0, 0, 0); PG8_LDB(B1, 0, 1); PG8_SCHED; PG8_LDA(At, 0, 0); PG8_STAGE(PG8_SA(1, 1), a1 + hstepA, voffA);
;             PG8_WAIT_V(8); PG8_WAIT_L(0); PG8_BAR; PG8_MMA(0, 0, At, B0); PG8_MMA(0, 1, At, B1); PG8_BAR; PG8_SCHED;
;             PG8_LDA(At, 0, 1); PG8_STAGE(PG8_SB(0, 0), b2, voffB); PG8_STAGE(PG8_SB(0, 1), b2 + hstepB, voffB); PG8_STAGE(PG8_SA(0, 0), a2, voffA);
;             PG8_WAIT_V(8); PG8_WAIT_L(0); PG8_BAR; PG8_MMA(1, 0, At, B0); PG8_MMA(1, 1, At, B1); PG8_BAR; PG8_SCHED;
.LBB0_708:
	s_add_i32 s88, s18, 2
	s_add_u32 s89, s86, 0x80
	s_addc_u32 s19, s87, 0
	s_add_i32 s90, 0, 0x10000
	s_cmp_eq_u32 s43, s18
	s_cselect_b32 s19, s71, s19
	s_cselect_b32 s18, s70, s89
	s_cselect_b32 vcc_hi, s85, s21
	s_cselect_b32 vcc_lo, s84, s20
	s_add_i32 s89, 0, 0x14000
	v_add_u32_e32 v142, s90, v202
	v_add_u32_e32 v158, s89, v202
	ds_read_b128 v[130:133], v142
	ds_read_b128 v[134:137], v142 offset:1024
	ds_read_b128 v[138:141], v142 offset:2048
	ds_read_b128 v[142:145], v142 offset:3072
	ds_read_b128 v[146:149], v158
	ds_read_b128 v[150:153], v158 offset:1024
	ds_read_b128 v[154:157], v158 offset:2048
	ds_read_b128 v[158:161], v158 offset:3072
	v_lshl_add_u64 v[234:235], s[86:87], 0, v[198:199]
	s_add_i32 m0, s31, 0xc000
	ds_read_b128 v[162:165], v204
	ds_read_b128 v[166:169], v204 offset:1024
	ds_read_b128 v[170:173], v204 offset:2048
	ds_read_b128 v[206:209], v204 offset:3072
	ds_read_b128 v[218:221], v204 offset:4096
	ds_read_b128 v[222:225], v204 offset:5120
	ds_read_b128 v[226:229], v204 offset:6144
	ds_read_b128 v[230:233], v204 offset:7168
	global_load_lds_dwordx4 v[234:235], off
	v_lshl_add_u64 v[234:235], s[86:87], 0, v[200:201]
	s_add_i32 m0, s31, 0xe000
	s_nop 0
	global_load_lds_dwordx4 v[234:235], off
	s_waitcnt vmcnt(8)
	s_waitcnt lgkmcnt(0)
	s_barrier
	s_waitcnt lgkmcnt(0)
	v_mfma_f32_16x16x32_bf16 v[34:37], v[130:133], v[162:165], v[34:37]
	v_mfma_f32_16x16x32_bf16 v[110:113], v[138:141], v[162:165], v[110:113]
	v_mfma_f32_16x16x32_bf16 v[22:25], v[130:133], v[170:173], v[22:25]
	v_mfma_f32_16x16x32_bf16 v[98:101], v[138:141], v[170:173], v[98:101]
	v_mfma_f32_16x16x32_bf16 v[14:17], v[130:133], v[218:221], v[14:17]
	v_mfma_f32_16x16x32_bf16 v[86:89], v[138:141], v[218:221], v[86:89]
	v_mfma_f32_16x16x32_bf16 v[10:13], v[130:133], v[226:229], v[10:13]
	v_mfma_f32_16x16x32_bf16 v[74:77], v[138:141], v[226:229], v[74:77]
	v_mfma_f32_16x16x32_bf16 v[34:37], v[134:137], v[166:169], v[34:37]
	v_mfma_f32_16x16x32_bf16 v[110:113], v[142:145], v[166:169], v[110:113]
	v_mfma_f32_16x16x32_bf16 v[22:25], v[134:137], v[206:209], v[22:25]
	v_mfma_f32_16x16x32_bf16 v[98:101], v[142:145], v[206:209], v[98:101]
	v_mfma_f32_16x16x32_bf16 v[14:17], v[134:137], v[222:225], v[14:17]
	v_mfma_f32_16x16x32_bf16 v[86:89], v[142:145], v[222:225], v[86:89]
	v_mfma_f32_16x16x32_bf16 v[10:13], v[134:137], v[230:233], v[10:13]
	v_mfma_f32_16x16x32_bf16 v[74:77], v[142:145], v[230:233], v[74:77]
	v_mfma_f32_16x16x32_bf16 v[118:121], v[146:149], v[162:165], v[118:121]
	v_mfma_f32_16x16x32_bf16 v[126:129], v[154:157], v[162:165], v[126:129]
	v_mfma_f32_16x16x32_bf16 v[106:109], v[146:149], v[170:173], v[106:109]
	v_mfma_f32_16x16x32_bf16 v[122:125], v[154:157], v[170:173], v[122:125]
	v_mfma_f32_16x16x32_bf16 v[94:97], v[146:149], v[218:221], v[94:97]
	v_mfma_f32_16x16x32_bf16 v[114:117], v[154:157], v[218:221], v[114:117]
	v_mfma_f32_16x16x32_bf16 v[82:85], v[146:149], v[226:229], v[82:85]
	v_mfma_f32_16x16x32_bf16 v[102:105], v[154:157], v[226:229], v[102:105]
	v_mfma_f32_16x16x32_bf16 v[118:121], v[150:153], v[166:169], v[118:121]
	v_mfma_f32_16x16x32_bf16 v[126:129], v[158:161], v[166:169], v[126:129]
	v_mfma_f32_16x16x32_bf16 v[106:109], v[150:153], v[206:209], v[106:109]
	v_mfma_f32_16x16x32_bf16 v[122:125], v[158:161], v[206:209], v[122:125]
	v_mfma_f32_16x16x32_bf16 v[94:97], v[150:153], v[222:225], v[94:97]
	v_mfma_f32_16x16x32_bf16 v[114:117], v[158:161], v[222:225], v[114:117]
	v_mfma_f32_16x16x32_bf16 v[82:85], v[150:153], v[230:233], v[82:85]
	v_mfma_f32_16x16x32_bf16 v[102:105], v[158:161], v[230:233], v[102:105]
	s_barrier
	s_add_i32 s90, s90, s30
	v_lshl_add_u64 v[234:235], vcc, 0, v[192:193]
	s_mov_b32 m0, s90
	ds_read_b128 v[162:165], v204 offset:16384
	ds_read_b128 v[166:169], v204 offset:17408
	ds_read_b128 v[170:173], v204 offset:18432
	ds_read_b128 v[206:209], v204 offset:19456
	ds_read_b128 v[218:221], v204 offset:20480
	ds_read_b128 v[222:225], v204 offset:21504
	ds_read_b128 v[226:229], v204 offset:22528
	ds_read_b128 v[230:233], v204 offset:23552
	global_load_lds_dwordx4 v[234:235], off
	s_add_i32 m0, s90, 0x2000
	v_lshl_add_u64 v[236:237], vcc, 0, v[196:197]
	s_add_u32 vcc_lo, vcc_lo, s9
	s_addc_u32 vcc_hi, vcc_hi, 0
	s_add_i32 s89, s89, s30
	global_load_lds_dwordx4 v[236:237], off
	v_lshl_add_u64 v[238:239], vcc, 0, v[192:193]
	s_mov_b32 m0, s89
	v_lshl_add_u64 v[240:241], vcc, 0, v[196:197]
	global_load_lds_dwordx4 v[238:239], off
	s_add_i32 m0, s89, 0x2000
	v_lshl_add_u64 v[242:243], s[18:19], 0, v[190:191]
	global_load_lds_dwordx4 v[240:241], off
	s_mov_b32 m0, s31
	v_lshl_add_u64 v[244:245], s[18:19], 0, v[194:195]
	global_load_lds_dwordx4 v[242:243], off
	s_mov_b32 m0, s34
	s_nop 0
	global_load_lds_dwordx4 v[244:245], off
	s_waitcnt vmcnt(8)
	s_waitcnt lgkmcnt(0)
	s_barrier
; #define PG8_STAGE(bufoff, gbase, voff) do { _Pragma("unroll") for (int _i = 0; _i < 2; ++_i) \
;         __builtin_amdgcn_global_load_lds((const unsigned*)((const char*)(gbase) + (voff)[_i]), (LAS unsigned*)(lds + (bufoff) + ldsw + _i * 8192), 16, 0, 0); } while (0)
; #define PG8_LDA(dst, b, h) do { _Pragma("unroll") for (int m = 0; m < 4; ++m) _Pragma("unroll") for (int k = 0; k < 2; ++k) dst[m][k] = *(const LAS bf16x8*)(lds + PG8_SA(b, h) + aoff + m * 2048 + k * 1024); } while (0)
; #define PG8_LDB(dst, b, h) do { _Pragma("unroll") for (int n = 0; n < 2; ++n) _Pragma("unroll") for (int k = 0; k < 2; ++k) dst[n][k] = *(const LAS bf16x8*)(lds + PG8_SB(b, h) + boff + n * 2048 + k * 1024); } while (0)
; #define PG8_MMA(ai, bj, At, Bt) do { __builtin_amdgcn_s_setprio(1); _Pragma("unroll") for (int m = 0; m < 4; ++m) _Pragma("unroll") for (int n = 0; n < 2; ++n) _Pragma("unroll") for (int k = 0; k < 2; ++k) \
;         acc[ai][bj][m][n] = __builtin_amdgcn_mfma_f32_16x16x32_bf16(Bt[n][k], At[m][k], acc[ai][bj][m][n], 0, 0, 0); __builtin_amdgcn_s_setprio(0); } while (0)
; #define PG8_WAIT_V(n) asm volatile("s_waitcnt vmcnt(" #n ")" ::: "memory")
; #define PG8_WAIT_L(n) asm volatile("s_waitcnt lgkmcnt(" #n ")" ::: "memory")
; #define PG8_BAR __builtin_amdgcn_s_barrier()
; #define PG8_SCHED __builtin_amdgcn_sched_barrier(0)
; template <class Epi, class Sched>
; __device__ __forceinline__ void gemm_phase(LAS unsigned char* lds, const Gemm g, const Sched& S, const Epi& E) {
;     ...
;             PG8_LDA(At, 0, 1); PG8_STAGE(PG8_SB(0, 0), b2, voffB); PG8_STAGE(PG8_SB(0, 1), b2 + hstepB, voffB); PG8_STAGE(PG8_SA(0, 0), a2, voffA);
;             PG8_WAIT_V(8); PG8_WAIT_L(0); PG8_BAR; PG8_MMA(1, 0, At, B0); PG8_MMA(1, 1, At, B1); PG8_BAR; PG8_SCHED;
;             PG8_LDB(B0, 1, 0); PG8_LDB(B1, 1, 1); PG8_SCHED; PG8_LDA(At, 1, 0); PG8_STAGE(PG8_SA(0, 1), a2 + hstepA, voffA);
;             PG8_WAIT_V(8); PG8_WAIT_L(0); PG8_BAR; PG8_MMA(0, 0, At, B0); PG8_MMA(0, 1, At, B1); PG8_BAR; PG8_SCHED;
	s_waitcnt lgkmcnt(0)
	v_mfma_f32_16x16x32_bf16 v[6:9], v[130:133], v[162:165], v[6:9]
	v_mfma_f32_16x16x32_bf16 v[62:65], v[138:141], v[162:165], v[62:65]
	v_mfma_f32_16x16x32_bf16 v[2:5], v[130:133], v[170:173], v[2:5]
	v_mfma_f32_16x16x32_bf16 v[50:53], v[138:141], v[170:173], v[50:53]
	v_mfma_f32_16x16x32_bf16 v[26:29], v[130:133], v[218:221], v[26:29]
	v_mfma_f32_16x16x32_bf16 v[42:45], v[138:141], v[218:221], v[42:45]
	v_mfma_f32_16x16x32_bf16 v[18:21], v[130:133], v[226:229], v[18:21]
	v_mfma_f32_16x16x32_bf16 v[30:33], v[138:141], v[226:229], v[30:33]
	v_mfma_f32_16x16x32_bf16 v[6:9], v[134:137], v[166:169], v[6:9]
	v_mfma_f32_16x16x32_bf16 v[62:65], v[142:145], v[166:169], v[62:65]
	v_mfma_f32_16x16x32_bf16 v[2:5], v[134:137], v[206:209], v[2:5]
	v_mfma_f32_16x16x32_bf16 v[50:53], v[142:145], v[206:209], v[50:53]
	v_mfma_f32_16x16x32_bf16 v[26:29], v[134:137], v[222:225], v[26:29]
	v_mfma_f32_16x16x32_bf16 v[42:45], v[142:145], v[222:225], v[42:45]
	v_mfma_f32_16x16x32_bf16 v[18:21], v[134:137], v[230:233], v[18:21]
	v_mfma_f32_16x16x32_bf16 v[30:33], v[142:145], v[230:233], v[30:33]
	v_mfma_f32_16x16x32_bf16 v[70:73], v[146:149], v[162:165], v[70:73]
	v_mfma_f32_16x16x32_bf16 v[90:93], v[154:157], v[162:165], v[90:93]
	v_mfma_f32_16x16x32_bf16 v[58:61], v[146:149], v[170:173], v[58:61]
	v_mfma_f32_16x16x32_bf16 v[78:81], v[154:157], v[170:173], v[78:81]
	v_mfma_f32_16x16x32_bf16 v[46:49], v[146:149], v[218:221], v[46:49]
	v_mfma_f32_16x16x32_bf16 v[66:69], v[154:157], v[218:221], v[66:69]
	v_mfma_f32_16x16x32_bf16 v[38:41], v[146:149], v[226:229], v[38:41]
	v_mfma_f32_16x16x32_bf16 v[54:57], v[154:157], v[226:229], v[54:57]
	v_mfma_f32_16x16x32_bf16 v[70:73], v[150:153], v[166:169], v[70:73]
	v_mfma_f32_16x16x32_bf16 v[90:93], v[158:161], v[166:169], v[90:93]
	v_mfma_f32_16x16x32_bf16 v[58:61], v[150:153], v[206:209], v[58:61]
	v_mfma_f32_16x16x32_bf16 v[78:81], v[158:161], v[206:209], v[78:81]
	v_mfma_f32_16x16x32_bf16 v[46:49], v[150:153], v[222:225], v[46:49]
	v_mfma_f32_16x16x32_bf16 v[66:69], v[158:161], v[222:225], v[66:69]
	v_mfma_f32_16x16x32_bf16 v[38:41], v[150:153], v[230:233], v[38:41]
	v_mfma_f32_16x16x32_bf16 v[54:57], v[158:161], v[230:233], v[54:57]
	s_barrier
	s_add_i32 s89, 0, 0x18000
	s_add_i32 s90, 0, 0x1c000
	v_add_u32_e32 v142, s89, v202
	v_add_u32_e32 v158, s90, v202
	ds_read_b128 v[130:133], v142
	ds_read_b128 v[134:137], v142 offset:1024
	ds_read_b128 v[138:141], v142 offset:2048
	ds_read_b128 v[142:145], v142 offset:3072
	ds_read_b128 v[146:149], v158
	ds_read_b128 v[150:153], v158 offset:1024
	ds_read_b128 v[154:157], v158 offset:2048
	ds_read_b128 v[158:161], v158 offset:3072
	s_add_u32 s18, s18, s80
	s_addc_u32 s19, s19, 0
	s_mov_b32 m0, s35
	v_lshl_add_u64 v[246:247], s[18:19], 0, v[190:191]
	ds_read_b128 v[162:165], v204 offset:32768
	ds_read_b128 v[166:169], v204 offset:33792
	ds_read_b128 v[170:173], v204 offset:34816
	ds_read_b128 v[206:209], v204 offset:35840
	ds_read_b128 v[218:221], v204 offset:36864
	ds_read_b128 v[222:225], v204 offset:37888
	ds_read_b128 v[226:229], v204 offset:38912
	ds_read_b128 v[230:233], v204 offset:39936
	global_load_lds_dwordx4 v[246:247], off
	v_lshl_add_u64 v[246:247], s[18:19], 0, v[194:195]
	s_mov_b32 m0, s40
	s_nop 0
	global_load_lds_dwordx4 v[246:247], off
	s_waitcnt vmcnt(8)
	s_waitcnt lgkmcnt(0)
	s_barrier
	s_waitcnt lgkmcnt(0)
	v_mfma_f32_16x16x32_bf16 v[34:37], v[130:133], v[162:165], v[34:37]
	v_mfma_f32_16x16x32_bf16 v[110:113], v[138:141], v[162:165], v[110:113]
	v_mfma_f32_16x16x32_bf16 v[22:25], v[130:133], v[170:173], v[22:25]
	v_mfma_f32_16x16x32_bf16 v[98:101], v[138:141], v[170:173], v[98:101]
	v_mfma_f32_16x16x32_bf16 v[14:17], v[130:133], v[218:221], v[14:17]
	v_mfma_f32_16x16x32_bf16 v[86:89], v[138:141], v[218:221], v[86:89]
	v_mfma_f32_16x16x32_bf16 v[10:13], v[130:133], v[226:229], v[10:13]
	v_mfma_f32_16x16x32_bf16 v[74:77], v[138:141], v[226:229], v[74:77]
	v_mfma_f32_16x16x32_bf16 v[34:37], v[134:137], v[166:169], v[34:37]
	v_mfma_f32_16x16x32_bf16 v[110:113], v[142:145], v[166:169], v[110:113]
	v_mfma_f32_16x16x32_bf16 v[22:25], v[134:137], v[206:209], v[22:25]
	v_mfma_f32_16x16x32_bf16 v[98:101], v[142:145], v[206:209], v[98:101]
	v_mfma_f32_16x16x32_bf16 v[14:17], v[134:137], v[222:225], v[14:17]
	v_mfma_f32_16x16x32_bf16 v[86:89], v[142:145], v[222:225], v[86:89]
	v_mfma_f32_16x16x32_bf16 v[10:13], v[134:137], v[230:233], v[10:13]
	v_mfma_f32_16x16x32_bf16 v[74:77], v[142:145], v[230:233], v[74:77]
	v_mfma_f32_16x16x32_bf16 v[118:121], v[146:149], v[162:165], v[118:121]
	v_mfma_f32_16x16x32_bf16 v[126:129], v[154:157], v[162:165], v[126:129]
	v_mfma_f32_16x16x32_bf16 v[106:109], v[146:149], v[170:173], v[106:109]
	v_mfma_f32_16x16x32_bf16 v[122:125], v[154:157], v[170:173], v[122:125]
	v_mfma_f32_16x16x32_bf16 v[94:97], v[146:149], v[218:221], v[94:97]
	v_mfma_f32_16x16x32_bf16 v[114:117], v[154:157], v[218:221], v[114:117]
	v_mfma_f32_16x16x32_bf16 v[82:85], v[146:149], v[226:229], v[82:85]
	v_mfma_f32_16x16x32_bf16 v[102:105], v[154:157], v[226:229], v[102:105]
	v_mfma_f32_16x16x32_bf16 v[118:121], v[150:153], v[166:169], v[118:121]
	v_mfma_f32_16x16x32_bf16 v[126:129], v[158:161], v[166:169], v[126:129]
	v_mfma_f32_16x16x32_bf16 v[106:109], v[150:153], v[206:209], v[106:109]
	v_mfma_f32_16x16x32_bf16 v[122:125], v[158:161], v[206:209], v[122:125]
	v_mfma_f32_16x16x32_bf16 v[94:97], v[150:153], v[222:225], v[94:97]
	v_mfma_f32_16x16x32_bf16 v[114:117], v[158:161], v[222:225], v[114:117]
	v_mfma_f32_16x16x32_bf16 v[82:85], v[150:153], v[230:233], v[82:85]
	v_mfma_f32_16x16x32_bf16 v[102:105], v[158:161], v[230:233], v[102:105]
	s_barrier
; #define PG8_STAGE(bufoff, gbase, voff) do { _Pragma("unroll") for (int _i = 0; _i < 2; ++_i) \
;         __builtin_amdgcn_global_load_lds((const unsigned*)((const char*)(gbase) + (voff)[_i]), (LAS unsigned*)(lds + (bufoff) + ldsw + _i * 8192), 16, 0, 0); } while (0)
; #define PG8_LDA(dst, b, h) do { _Pragma("unroll") for (int m = 0; m < 4; ++m) _Pragma("unroll") for (int k = 0; k < 2; ++k) dst[m][k] = *(const LAS bf16x8*)(lds + PG8_SA(b, h) + aoff + m * 2048 + k * 1024); } while (0)
; #define PG8_MMA(ai, bj, At, Bt) do { __builtin_amdgcn_s_setprio(1); _Pragma("unroll") for (int m = 0; m < 4; ++m) _Pragma("unroll") for (int n = 0; n < 2; ++n) _Pragma("unroll") for (int k = 0; k < 2; ++k) \
;         acc[ai][bj][m][n] = __builtin_amdgcn_mfma_f32_16x16x32_bf16(Bt[n][k], At[m][k], acc[ai][bj][m][n], 0, 0, 0); __builtin_amdgcn_s_setprio(0); } while (0)
; #define PG8_WAIT_V(n) asm volatile("s_waitcnt vmcnt(" #n ")" ::: "memory")
; #define PG8_WAIT_L(n) asm volatile("s_waitcnt lgkmcnt(" #n ")" ::: "memory")
; #define PG8_BAR __builtin_amdgcn_s_barrier()
; #define PG8_SCHED __builtin_amdgcn_sched_barrier(0)
; template <class Epi, class Sched>
; __device__ __forceinline__ void gemm_phase(LAS unsigned char* lds, const Gemm g, const Sched& S, const Epi& E) {
;     ...
;             PG8_LDA(At, 1, 1); PG8_STAGE(PG8_SB(1, 0), b3, voffB); PG8_STAGE(PG8_SB(1, 1), b3 + hstepB, voffB); PG8_STAGE(PG8_SA(1, 0), a3, voffA);
;             PG8_WAIT_V(8); PG8_WAIT_L(0); PG8_BAR; PG8_MMA(1, 0, At, B0); PG8_MMA(1, 1, At, B1); PG8_BAR; PG8_SCHED;
;         }
	s_add_i32 s18, s89, s30
	v_lshl_add_u64 v[234:235], v[234:235], 0, s[62:63]
	s_mov_b32 m0, s18
	ds_read_b128 v[162:165], v204 offset:49152
	ds_read_b128 v[166:169], v204 offset:50176
	ds_read_b128 v[170:173], v204 offset:51200
	ds_read_b128 v[206:209], v204 offset:52224
	ds_read_b128 v[218:221], v204 offset:53248
	ds_read_b128 v[222:225], v204 offset:54272
	ds_read_b128 v[226:229], v204 offset:55296
	ds_read_b128 v[230:233], v204 offset:56320
	global_load_lds_dwordx4 v[234:235], off
	v_lshl_add_u64 v[234:235], v[236:237], 0, s[62:63]
	s_add_i32 m0, s18, 0x2000
	s_add_i32 s18, s90, s30
	global_load_lds_dwordx4 v[234:235], off
	v_lshl_add_u64 v[234:235], v[238:239], 0, s[62:63]
	s_mov_b32 m0, s18
	s_nop 0
	global_load_lds_dwordx4 v[234:235], off
	v_lshl_add_u64 v[234:235], v[240:241], 0, s[62:63]
	s_add_i32 m0, s18, 0x2000
	s_nop 0
	global_load_lds_dwordx4 v[234:235], off
	v_lshl_add_u64 v[234:235], v[242:243], 0, s[62:63]
	s_mov_b32 m0, s41
	s_nop 0
	global_load_lds_dwordx4 v[234:235], off
	v_lshl_add_u64 v[234:235], v[244:245], 0, s[62:63]
	s_mov_b32 m0, s42
	s_nop 0
	global_load_lds_dwordx4 v[234:235], off
	s_waitcnt vmcnt(8)
	s_waitcnt lgkmcnt(0)
	s_barrier
	s_waitcnt lgkmcnt(0)
	v_mfma_f32_16x16x32_bf16 v[6:9], v[130:133], v[162:165], v[6:9]
	v_mfma_f32_16x16x32_bf16 v[62:65], v[138:141], v[162:165], v[62:65]
	v_mfma_f32_16x16x32_bf16 v[2:5], v[130:133], v[170:173], v[2:5]
	v_mfma_f32_16x16x32_bf16 v[50:53], v[138:141], v[170:173], v[50:53]
	v_mfma_f32_16x16x32_bf16 v[26:29], v[130:133], v[218:221], v[26:29]
	v_mfma_f32_16x16x32_bf16 v[42:45], v[138:141], v[218:221], v[42:45]
	v_mfma_f32_16x16x32_bf16 v[18:21], v[130:133], v[226:229], v[18:21]
	v_mfma_f32_16x16x32_bf16 v[30:33], v[138:141], v[226:229], v[30:33]
	v_mfma_f32_16x16x32_bf16 v[6:9], v[134:137], v[166:169], v[6:9]
	v_mfma_f32_16x16x32_bf16 v[62:65], v[142:145], v[166:169], v[62:65]
	v_mfma_f32_16x16x32_bf16 v[2:5], v[134:137], v[206:209], v[2:5]
	v_mfma_f32_16x16x32_bf16 v[50:53], v[142:145], v[206:209], v[50:53]
	v_mfma_f32_16x16x32_bf16 v[26:29], v[134:137], v[222:225], v[26:29]
	v_mfma_f32_16x16x32_bf16 v[42:45], v[142:145], v[222:225], v[42:45]
	v_mfma_f32_16x16x32_bf16 v[18:21], v[134:137], v[230:233], v[18:21]
	v_mfma_f32_16x16x32_bf16 v[30:33], v[142:145], v[230:233], v[30:33]
	v_mfma_f32_16x16x32_bf16 v[70:73], v[146:149], v[162:165], v[70:73]
	v_mfma_f32_16x16x32_bf16 v[90:93], v[154:157], v[162:165], v[90:93]
	v_mfma_f32_16x16x32_bf16 v[58:61], v[146:149], v[170:173], v[58:61]
	v_mfma_f32_16x16x32_bf16 v[78:81], v[154:157], v[170:173], v[78:81]
	v_mfma_f32_16x16x32_bf16 v[46:49], v[146:149], v[218:221], v[46:49]
	v_mfma_f32_16x16x32_bf16 v[66:69], v[154:157], v[218:221], v[66:69]
	v_mfma_f32_16x16x32_bf16 v[38:41], v[146:149], v[226:229], v[38:41]
	v_mfma_f32_16x16x32_bf16 v[54:57], v[154:157], v[226:229], v[54:57]
	v_mfma_f32_16x16x32_bf16 v[70:73], v[150:153], v[166:169], v[70:73]
	v_mfma_f32_16x16x32_bf16 v[90:93], v[158:161], v[166:169], v[90:93]
	v_mfma_f32_16x16x32_bf16 v[58:61], v[150:153], v[206:209], v[58:61]
	v_mfma_f32_16x16x32_bf16 v[78:81], v[158:161], v[206:209], v[78:81]
	v_mfma_f32_16x16x32_bf16 v[46:49], v[150:153], v[222:225], v[46:49]
	v_mfma_f32_16x16x32_bf16 v[66:69], v[158:161], v[222:225], v[66:69]
	v_mfma_f32_16x16x32_bf16 v[38:41], v[150:153], v[230:233], v[38:41]
	v_mfma_f32_16x16x32_bf16 v[54:57], v[158:161], v[230:233], v[54:57]
	s_barrier
	s_add_u32 s86, s86, 0x100
	s_addc_u32 s87, s87, 0
	s_add_u32 s20, s20, 0x100
	s_addc_u32 s21, s21, 0
	s_cmp_ge_u32 s88, s1
	s_mov_b32 s18, s88
	s_cbranch_scc0 .LBB0_708
	s_and_b64 vcc, exec, s[36:37]
	s_cbranch_vccz .LBB0_711
	s_barrier
